# attention queue order changed to batch-major (all query blocks of a batch adjacent) for K/V L2 reuse
# baseline (speedup 1.0000x reference)
; __device__ __forceinline__ void unpack8(u32x4v w, float* f) { f[0] = bflo(w.x); f[1] = bfhi(w.x); f[2] = bflo(w.y); f[3] = bfhi(w.y); f[4] = bflo(w.z); f[5] = bfhi(w.z); f[6] = bflo(w.w); f[7] = bfhi(w.w); }
; __device__ __forceinline__ void attn_unit(const Args& c, int l, int b, int h, int qb, float lam, float lam_init, LAS unsigned char* lds) {
;     ...
;         const bf16* qrow = P + (seq0 + 128 * qb + 16 * w + r) * PW + QC;
; #pragma unroll
;         for (int m = 0; m < 2; ++m) {
;             float f[16];
;             unpack8(*(const u32x4v*)(qrow + m * 64 + q4 * 8), f); unpack8(*(const u32x4v*)(qrow + m * 64 + 32 + q4 * 8), f + 8);
;             float ss = 0.f;
; #pragma unroll
;             for (int e = 0; e < 16; ++e) ss += f[e] * f[e];
;             ss += __shfl_xor(ss, 16); ss += __shfl_xor(ss, 32);
; __device__ __forceinline__ void m2_phase(const Args& c, int l, LAS unsigned char* lds, int G, int mode, bool dry, int cidx) {
;     ...
;             const int q = *slot;
;             if (q >= 128) break;
;             const int qb = 15 - (q >> 3);
.LBB0_243:
	s_or_b64 exec, exec, s[2:3]
	v_mov_b32_e32 v0, s39
	s_waitcnt lgkmcnt(0)
	s_barrier
	ds_read_b32 v0, v0
	s_movk_i32 s2, 0x7f
	s_waitcnt lgkmcnt(0)
	v_cmp_lt_i32_e32 vcc, s2, v0
	v_readfirstlane_b32 s4, v0
	s_mov_b64 s[2:3], -1
	s_cbranch_vccnz .LBB0_240
	v_readlane_b32 s8, v252, 57
	s_and_b32 s6, s4, 15
	v_readlane_b32 s10, v252, 59
	v_readlane_b32 s11, v252, 60
	s_sub_i32 s22, 15, s6
	v_mov_b32_e32 v106, v179
	s_mov_b64 s[38:39], s[10:11]
	v_readlane_b32 s9, v252, 58
	s_mov_b32 s8, 0
	s_add_u32 s2, s38, 0xa800000
	s_addc_u32 s3, s39, 0
	s_lshl_b32 s4, s4, 7
	s_ashr_i32 s9, s8, 31
	s_and_b32 s18, s4, 0x3800
	s_lshl_b64 s[4:5], s[8:9], 3
	v_readlane_b32 s8, v251, 0
	v_readlane_b32 s9, v251, 1
	s_add_u32 s24, s8, s4
	s_addc_u32 s25, s9, s5
	s_load_dwordx4 s[8:11], s[24:25], 0xb0
	v_readfirstlane_b32 s4, v106
	v_and_b32_e32 v107, 15, v106
	v_mov_b64_e32 v[18:19], s[2:3]
	v_bfe_u32 v108, v106, 4, 2
	s_waitcnt lgkmcnt(0)
	s_add_u32 s12, s8, s30
	s_addc_u32 s13, s9, s31
	s_ashr_i32 s4, s4, 2
	s_lshl_b32 s7, s22, 7
	s_and_b32 s8, s4, -16
	s_add_i32 s5, s7, s18
	s_ashr_i32 s4, s8, 31
	s_add_u32 s5, s8, s5
	v_or_b32_e32 v184, s5, v107
	s_addc_u32 s9, s4, 0
	v_mad_u64_u32 v[2:3], s[4:5], v184, s27, v[18:19]
	v_mad_i32_i24 v3, s9, v196, v3
	s_lshl_b32 s4, s19, 1
	s_mov_b32 s5, s15
	v_lshl_add_u64 v[2:3], v[2:3], 0, s[4:5]
	v_lshlrev_b32_e32 v0, 4, v108
	v_lshl_add_u64 v[2:3], v[2:3], 0, v[0:1]
	s_movk_i32 s5, 0x1000
	v_add_co_u32_e32 v2, vcc, s5, v2
	v_lshlrev_b32_e32 v14, 5, v108
	s_nop 0
	v_addc_co_u32_e32 v3, vcc, 0, v3, vcc
	flat_load_dwordx4 v[26:29], v[2:3] offset:3904
	flat_load_dwordx4 v[30:33], v[2:3] offset:4032
	flat_load_dwordx4 v[34:37], v[2:3] offset:3840
	flat_load_dwordx4 v[38:41], v[2:3] offset:3968
	s_nop 0
	global_load_dwordx4 v[2:5], v14, s[12:13] offset:144
	global_load_dwordx4 v[6:9], v14, s[12:13] offset:128
	global_load_dwordx4 v[10:13], v14, s[12:13] offset:16
	s_nop 0
	global_load_dwordx4 v[14:17], v14, s[12:13]
	v_ashrrev_i32_e32 v186, 3, v106
	s_lshl_b32 s20, s0, 1
	s_mov_b32 s21, s15
	s_lshl_b32 s28, s1, 1
	s_mov_b32 s29, s15
	s_add_u32 s10, s10, s30
	s_addc_u32 s11, s11, s31
	v_lshlrev_b32_e32 v208, 2, v108
	s_add_i32 s8, s8, s7
	s_movk_i32 s7, 0x110
	v_or_b32_e32 v209, s8, v107
	v_mov_b32_e32 v108, v1
	v_mov_b32_e32 v109, v1
	s_mov_b32 s5, 0
	v_mov_b32_e32 v185, s9
	v_ashrrev_i32_e32 v187, 31, v186
	s_sub_i32 s34, 16, s6
	v_mov_b32_e32 v216, 0
	v_mov_b32_e32 v192, 0xff800000
	v_mov_b32_e32 v148, 0xff800000
	v_mov_b32_e32 v215, 0
	s_mov_b32 s35, 0
	s_waitcnt vmcnt(0) lgkmcnt(0)
	v_lshlrev_b32_e32 v42, 16, v29
	v_and_b32_e32 v43, 0xffff0000, v29
	v_lshlrev_b32_e32 v20, 16, v33
	v_and_b32_e32 v21, 0xffff0000, v33
	v_lshlrev_b32_e32 v44, 16, v28
	v_and_b32_e32 v45, 0xffff0000, v28
	v_lshlrev_b32_e32 v22, 16, v32
	v_and_b32_e32 v23, 0xffff0000, v32
	v_lshlrev_b32_e32 v28, 16, v27
	v_and_b32_e32 v29, 0xffff0000, v27
	v_lshlrev_b32_e32 v24, 16, v31
	v_and_b32_e32 v25, 0xffff0000, v31
	v_lshlrev_b32_e32 v32, 16, v26
	v_and_b32_e32 v33, 0xffff0000, v26
	v_lshlrev_b32_e32 v26, 16, v30
	v_and_b32_e32 v27, 0xffff0000, v30
	v_lshlrev_b32_e32 v30, 16, v37
	v_and_b32_e32 v31, 0xffff0000, v37
	v_lshlrev_b32_e32 v46, 16, v41
	v_and_b32_e32 v47, 0xffff0000, v41
	v_lshlrev_b32_e32 v48, 16, v36
	v_and_b32_e32 v49, 0xffff0000, v36
	v_lshlrev_b32_e32 v36, 16, v40
	v_and_b32_e32 v37, 0xffff0000, v40
	v_lshlrev_b32_e32 v40, 16, v35
	v_and_b32_e32 v41, 0xffff0000, v35
	v_and_b32_e32 v51, 0xffff0000, v34
	v_and_b32_e32 v35, 0xffff0000, v38
	v_lshlrev_b32_e32 v50, 16, v34
	v_lshlrev_b32_e32 v34, 16, v38
	v_mov_b32_e32 v82, v35
	v_mov_b32_e32 v83, v51
	v_lshlrev_b32_e32 v58, 16, v39
	v_mov_b32_e32 v80, v34
	v_mov_b32_e32 v81, v50
	v_pk_mul_f32 v[82:83], v[82:83], v[82:83]
	v_and_b32_e32 v59, 0xffff0000, v39
	v_mov_b32_e32 v76, v58
	v_mov_b32_e32 v77, v40
	v_pk_fma_f32 v[80:81], v[80:81], v[80:81], v[82:83]
	v_mov_b32_e32 v78, v59
	v_mov_b32_e32 v79, v41
	v_pk_fma_f32 v[76:77], v[76:77], v[76:77], v[80:81]
	v_mov_b32_e32 v72, v36
	v_mov_b32_e32 v73, v48
	v_pk_fma_f32 v[76:77], v[78:79], v[78:79], v[76:77]
	v_mov_b32_e32 v74, v37
	v_mov_b32_e32 v75, v49
	v_pk_fma_f32 v[72:73], v[72:73], v[72:73], v[76:77]
	v_mov_b32_e32 v68, v46
	v_mov_b32_e32 v69, v30
	v_pk_fma_f32 v[72:73], v[74:75], v[74:75], v[72:73]
	v_pk_mul_f32 v[64:65], v[32:33], v[32:33]
	v_pk_mul_f32 v[66:67], v[26:27], v[26:27]
	v_mov_b32_e32 v70, v47
	v_mov_b32_e32 v71, v31
	v_pk_fma_f32 v[68:69], v[68:69], v[68:69], v[72:73]
	v_pk_mul_f32 v[60:61], v[28:29], v[28:29]
	v_pk_fma_f32 v[68:69], v[70:71], v[70:71], v[68:69]
	v_mov_b32_e32 v70, v66
	v_mov_b32_e32 v71, v64
	v_pk_mul_f32 v[62:63], v[24:25], v[24:25]
	v_pk_add_f32 v[68:69], v[70:71], v[68:69]
	v_mov_b32_e32 v64, v67
	v_pk_add_f32 v[64:65], v[64:65], v[68:69]
	v_mov_b32_e32 v66, v62
	v_mov_b32_e32 v67, v60
	v_pk_mul_f32 v[54:55], v[44:45], v[44:45]
	v_pk_mul_f32 v[56:57], v[22:23], v[22:23]
	v_pk_add_f32 v[64:65], v[66:67], v[64:65]
	v_mov_b32_e32 v60, v63
	v_pk_add_f32 v[60:61], v[60:61], v[64:65]
	v_mov_b32_e32 v62, v56
	v_mov_b32_e32 v63, v54
	v_pk_mul_f32 v[38:39], v[42:43], v[42:43]
	v_pk_mul_f32 v[52:53], v[20:21], v[20:21]
	v_pk_add_f32 v[60:61], v[62:63], v[60:61]
	v_mov_b32_e32 v54, v57
	v_pk_add_f32 v[54:55], v[54:55], v[60:61]
	v_mov_b32_e32 v56, v52
	v_mov_b32_e32 v57, v38
	v_pk_add_f32 v[54:55], v[56:57], v[54:55]
	v_mov_b32_e32 v38, v53
	v_pk_add_f32 v[38:39], v[38:39], v[54:55]
	ds_bpermute_b32 v53, v205, v39
	ds_bpermute_b32 v52, v205, v38
	s_waitcnt lgkmcnt(0)
; __device__ __forceinline__ unsigned pk2(float lo, float hi) { f32x2_t v = {lo, hi}; bf16x2_t b = __builtin_convertvector(v, bf16x2_t); return __builtin_bit_cast(unsigned, b); }
; #define ATT_FETCH(KT) do { _Pragma("unroll") for (int hh = 0; hh < 2; ++hh) { const bf16* krow = P + (seq0 + 128 * (KT) + 64 * hh + skey) * PW; \
;         gk0[hh] = *(const u32x4v*)(krow + KC + part * 16); gk1[hh] = *(const u32x4v*)(krow + KC + part * 16 + 8); \
;         gv0[hh] = *(const u32x4v*)(krow + VC + part * 16); gv1[hh] = *(const u32x4v*)(krow + VC + part * 16 + 8); } } while (0)
; __device__ __forceinline__ void attn_unit(const Args& c, int l, int b, int h, int qb, float lam, float lam_init, LAS unsigned char* lds) {
;     ...
; #pragma unroll
;             for (int e = 0; e < 16; ++e) ss += f[e] * f[e];
;             ss += __shfl_xor(ss, 16); ss += __shfl_xor(ss, 32);
;             const float sc = rsqrtf(ss * (1.f / 64.f) + 1e-6f) * (0.125f * 1.4426950408889634f);
; #pragma unroll
;             for (int ks = 0; ks < 2; ++ks) { u32x4v o; const float* g = f + 8 * ks; const float* wn = qnw + ks * 32 + q4 * 8;
;                 o.x = pk2(g[0] * sc * wn[0], g[1] * sc * wn[1]); o.y = pk2(g[2] * sc * wn[2], g[3] * sc * wn[3]); o.z = pk2(g[4] * sc * wn[4], g[5] * sc * wn[5]); o.w = pk2(g[6] * sc * wn[6], g[7] * sc * wn[7]);
;                 qf[m][ks] = __builtin_bit_cast(bf16x8, o); }
;         }
;     }
;     f32x4 O[2][8];
; #pragma unroll
;     for (int m = 0; m < 2; ++m)
; #pragma unroll
;         for (int vb = 0; vb < 8; ++vb) O[m][vb] = (f32x4){0.f, 0.f, 0.f, 0.f};
;     float mrow[2] = {-INFINITY, -INFINITY}, lrow[2] = {0.f, 0.f};
;     const int NT = qb + 1;
;     const int skey = tid >> 3, part = tid & 7;
;     const float* kwp = knw + (part & 3) * 16;
;     u32x4v gk0[2], gk1[2], gv0[2], gv1[2];
;     ...
;     ATT_FETCH(0);
	v_pk_add_f32 v[38:39], v[38:39], v[52:53]
	ds_bpermute_b32 v53, v206, v39
	ds_bpermute_b32 v52, v206, v38
	s_waitcnt lgkmcnt(0)
	v_pk_add_f32 v[38:39], v[38:39], v[52:53]
	s_nop 0
	v_pk_fma_f32 v[38:39], v[38:39], s[26:27], v[178:179] op_sel_hi:[1,0,0]
	s_nop 0
	v_mul_f32_e32 v52, 0x4b800000, v39
	v_cmp_gt_f32_e32 vcc, s33, v39
	s_nop 1
	v_cndmask_b32_e32 v39, v39, v52, vcc
	v_rsq_f32_e32 v39, v39
	s_nop 0
	v_mul_f32_e32 v52, 0x45800000, v39
	v_cndmask_b32_e32 v39, v39, v52, vcc
	v_mul_f32_e32 v52, 0x3e38aa3b, v39
	v_pk_mul_f32 v[28:29], v[52:53], v[28:29] op_sel_hi:[0,1]
	v_pk_mul_f32 v[32:33], v[52:53], v[32:33] op_sel_hi:[0,1]
	v_pk_mul_f32 v[28:29], v[8:9], v[28:29]
	v_pk_mul_f32 v[60:61], v[52:53], v[50:51] op_sel_hi:[0,1]
	v_pk_mul_f32 v[30:31], v[52:53], v[30:31] op_sel_hi:[0,1]
	v_pk_mul_f32 v[42:43], v[52:53], v[42:43] op_sel_hi:[0,1]
	v_cvt_pk_bf16_f32 v51, v28, v29
	v_pk_mul_f32 v[28:29], v[6:7], v[32:33]
	v_pk_mul_f32 v[48:49], v[52:53], v[48:49] op_sel_hi:[0,1]
	v_pk_mul_f32 v[44:45], v[52:53], v[44:45] op_sel_hi:[0,1]
	v_pk_mul_f32 v[42:43], v[4:5], v[42:43]
	v_cvt_pk_bf16_f32 v50, v28, v29
	v_pk_mul_f32 v[28:29], v[12:13], v[30:31]
	v_lshlrev_b32_e32 v30, 4, v106
	v_add_u32_e32 v39, s18, v186
	v_pk_mul_f32 v[40:41], v[52:53], v[40:41] op_sel_hi:[0,1]
	v_cvt_pk_bf16_f32 v53, v42, v43
	v_pk_mul_f32 v[42:43], v[2:3], v[44:45]
	v_cvt_pk_bf16_f32 v57, v28, v29
	v_pk_mul_f32 v[28:29], v[10:11], v[48:49]
	v_and_b32_e32 v30, 0x70, v30
	v_mad_i64_i32 v[32:33], s[12:13], v39, s27, v[18:19]
	v_cvt_pk_bf16_f32 v52, v42, v43
	v_cvt_pk_bf16_f32 v56, v28, v29
	v_pk_mul_f32 v[28:29], v[16:17], v[40:41]
	v_lshl_add_u64 v[40:41], v[32:33], 0, s[20:21]
	v_lshlrev_b32_e32 v42, 1, v30
	v_mov_b32_e32 v43, v1
	v_lshl_add_u64 v[32:33], v[32:33], 0, s[28:29]
	v_lshl_add_u64 v[40:41], v[40:41], 0, v[42:43]
	v_lshl_add_u64 v[32:33], v[32:33], 0, v[42:43]
	flat_load_dwordx4 v[66:69], v[40:41]
	flat_load_dwordx4 v[70:73], v[40:41] offset:16
	flat_load_dwordx4 v[78:81], v[32:33]
	flat_load_dwordx4 v[82:85], v[32:33] offset:16
	v_add_u32_e32 v32, 64, v39
	v_mad_i64_i32 v[18:19], s[12:13], v32, s27, v[18:19]
	v_lshl_add_u64 v[32:33], v[18:19], 0, s[20:21]
	v_lshl_add_u64 v[18:19], v[18:19], 0, s[28:29]
	v_lshl_add_u64 v[32:33], v[32:33], 0, v[42:43]
	v_lshl_add_u64 v[18:19], v[18:19], 0, v[42:43]
	flat_load_dwordx4 v[90:93], v[32:33]
	flat_load_dwordx4 v[94:97], v[32:33] offset:16
	flat_load_dwordx4 v[98:101], v[18:19]
	flat_load_dwordx4 v[102:105], v[18:19] offset:16
	v_mul_f32_e32 v31, 0x4b800000, v38
	v_cmp_gt_f32_e32 vcc, s33, v38
	v_cvt_pk_bf16_f32 v55, v28, v29
	s_nop 0
	v_cndmask_b32_e32 v18, v38, v31, vcc
	v_rsq_f32_e32 v31, v18
	v_pk_mul_f32 v[18:19], v[14:15], v[60:61]
	s_nop 0
	v_cvt_pk_bf16_f32 v54, v18, v19
	v_mul_f32_e32 v18, 0x45800000, v31
	v_cndmask_b32_e32 v18, v31, v18, vcc
	v_mul_f32_e32 v18, 0x3e38aa3b, v18
	v_pk_mul_f32 v[28:29], v[18:19], v[34:35] op_sel_hi:[0,1]
	v_pk_mul_f32 v[14:15], v[14:15], v[28:29]
	s_nop 0
	v_cvt_pk_bf16_f32 v74, v14, v15
	v_pk_mul_f32 v[14:15], v[18:19], v[58:59] op_sel_hi:[0,1]
	v_pk_mul_f32 v[14:15], v[16:17], v[14:15]
	s_nop 0
	v_cvt_pk_bf16_f32 v75, v14, v15
	v_pk_mul_f32 v[14:15], v[18:19], v[36:37] op_sel_hi:[0,1]
	v_pk_mul_f32 v[10:11], v[10:11], v[14:15]
	s_nop 0
	v_cvt_pk_bf16_f32 v76, v10, v11
	v_pk_mul_f32 v[10:11], v[18:19], v[46:47] op_sel_hi:[0,1]
	v_pk_mul_f32 v[10:11], v[12:13], v[10:11]
	s_nop 0
	v_cvt_pk_bf16_f32 v77, v10, v11
	v_pk_mul_f32 v[10:11], v[18:19], v[26:27] op_sel_hi:[0,1]
	v_pk_mul_f32 v[6:7], v[6:7], v[10:11]
	s_nop 0
	v_cvt_pk_bf16_f32 v86, v6, v7
	v_pk_mul_f32 v[6:7], v[18:19], v[24:25] op_sel_hi:[0,1]
	v_pk_mul_f32 v[6:7], v[8:9], v[6:7]
	s_nop 0
	v_cvt_pk_bf16_f32 v87, v6, v7
	v_pk_mul_f32 v[6:7], v[18:19], v[22:23] op_sel_hi:[0,1]
	v_pk_mul_f32 v[2:3], v[2:3], v[6:7]
	s_nop 0
	v_cvt_pk_bf16_f32 v88, v2, v3
	v_pk_mul_f32 v[2:3], v[18:19], v[20:21] op_sel_hi:[0,1]
	v_pk_mul_f32 v[2:3], v[4:5], v[2:3]
	s_nop 0
	v_cvt_pk_bf16_f32 v89, v2, v3
	v_lshlrev_b32_e32 v2, 6, v106
	v_and_b32_e32 v2, 0xc0, v2
	v_mov_b32_e32 v3, v1
	v_lshl_add_u64 v[188:189], s[10:11], 0, v[2:3]
	v_bfe_u32 v2, v106, 2, 2
	v_add_u32_e32 v3, 0, v0
	v_or_b32_e32 v0, v208, v2
	v_lshlrev_b32_e32 v2, 3, v106
	v_mul_u32_u24_e32 v0, 0x110, v0
	v_and_b32_e32 v2, 24, v2
	v_add3_u32 v210, 0, v0, v2
	v_mul_lo_u32 v0, v186, s7
	v_mul_u32_u24_e32 v2, 0x110, v107
	v_mov_b32_e32 v106, v1
	v_mov_b32_e32 v107, v1
	v_add3_u32 v211, 0, v42, v0
	v_lshlrev_b32_e32 v0, 1, v30
	v_add_u32_e32 v212, v3, v2
	v_mov_b64_e32 v[2:3], v[106:107]
	v_mov_b64_e32 v[10:11], v[106:107]
	v_mov_b64_e32 v[18:19], v[106:107]
	v_mov_b64_e32 v[58:59], v[106:107]
	v_mov_b64_e32 v[26:27], v[106:107]
	v_mov_b64_e32 v[34:35], v[106:107]
	v_mov_b64_e32 v[42:43], v[106:107]
	v_mov_b64_e32 v[112:113], v[108:109]
	v_mov_b64_e32 v[6:7], v[106:107]
	v_mov_b64_e32 v[14:15], v[106:107]
	v_mov_b64_e32 v[22:23], v[106:107]
	v_mov_b64_e32 v[62:63], v[106:107]
	v_mov_b64_e32 v[30:31], v[106:107]
	v_mov_b64_e32 v[38:39], v[106:107]
	v_mov_b64_e32 v[46:47], v[106:107]
	v_mov_b64_e32 v[4:5], v[108:109]
	v_mov_b64_e32 v[12:13], v[108:109]
	v_mov_b64_e32 v[20:21], v[108:109]
	v_mov_b64_e32 v[60:61], v[108:109]
	v_mov_b64_e32 v[28:29], v[108:109]
	v_mov_b64_e32 v[36:37], v[108:109]
	v_mov_b64_e32 v[44:45], v[108:109]
	v_mov_b64_e32 v[110:111], v[106:107]
	v_mov_b64_e32 v[8:9], v[108:109]
	v_mov_b64_e32 v[16:17], v[108:109]
	v_mov_b64_e32 v[24:25], v[108:109]
	v_mov_b64_e32 v[64:65], v[108:109]
	v_mov_b64_e32 v[32:33], v[108:109]
	v_mov_b64_e32 v[40:41], v[108:109]
	v_mov_b64_e32 v[48:49], v[108:109]
